# skinny GEMM: tile permutation so each XCD covers 4 row blocks x 8 column blocks (12 operand streams instead of 33)
# baseline (speedup 1.0000x reference)
.LBB0_1221:
	v_mbcnt_lo_u32_b32 v0, -1, 0
	v_mbcnt_hi_u32_b32 v0, -1, v0
	v_readlane_b32 s0, v254, 10
	s_cmpk_gt_i32 s2, 0xff
	s_nop 0
	v_add_u32_e32 v0, s0, v0
	s_mov_b32 s0, s75
	s_cbranch_scc1 .LBB0_1238
	v_ashrrev_i32_e32 v67, 4, v0
	s_waitcnt lgkmcnt(0)
	v_and_b32_e32 v1, 15, v0
	v_bfe_u32 v4, v0, 4, 2
	v_lshlrev_b32_e32 v0, 3, v0
	v_and_b32_e32 v0, 0x78, v0
	v_lshlrev_b32_e32 v60, 1, v0
	v_mov_b32_e32 v0, 0
	v_mov_b32_e32 v61, v0
	s_lshl_b32 s3, s0, 4
	s_lshl_b32 s0, s0, 3
	v_lshl_add_u64 v[2:3], s[80:81], 0, v[60:61]
	s_mov_b64 s[4:5], 0x4f890000
	s_and_b32 s3, s3, 48
	s_andn2_b32 s0, s0, 31
	v_lshl_add_u64 v[62:63], v[2:3], 0, s[4:5]
	s_movk_i32 s1, 0x88
	v_or_b32_e32 v3, s3, v1
	v_or_b32_e32 v6, s0, v1
	v_mul_lo_u32 v2, v67, s1
	v_mul_u32_u24_e32 v3, 0x88, v3
	v_lshlrev_b32_e32 v5, 3, v4
	v_mul_lo_u32 v7, v6, s1
	v_lshlrev_b32_e32 v68, 4, v1
	v_mbcnt_lo_u32_b32 v1, -1, 0
	v_lshl_add_u64 v[64:65], s[10:11], 0, v[60:61]
	v_add_u32_e32 v61, 0x2000, v6
	v_lshl_or_b32 v66, v4, 2, s3
	v_cmp_eq_u32_e64 s[0:1], 0, v4
	v_mov_b32_e32 v69, v0
	s_mov_b32 s3, 0x40000
	s_mov_b64 s[4:5], 0x300
	v_lshlrev_b32_e32 v74, 1, v2
	v_lshlrev_b32_e32 v75, 1, v3
	v_lshlrev_b32_e32 v76, 1, v5
	v_lshlrev_b32_e32 v77, 1, v7
	v_mbcnt_hi_u32_b32 v78, -1, v1
	s_and_b32 s98, s2, 7
	s_lshl_b32 s98, s98, 5
	s_lshr_b32 s12, s2, 3
	s_add_i32 s12, s12, s98
	s_branch .LBB0_1224

.LBB0_1538:
	v_mbcnt_lo_u32_b32 v0, -1, 0
	v_mbcnt_hi_u32_b32 v0, -1, v0
	v_readlane_b32 s0, v254, 10
	s_cmpk_gt_i32 s2, 0xff
	s_nop 0
	v_add_u32_e32 v0, s0, v0
	s_mov_b32 s0, s75
	s_cbranch_scc1 .LBB0_1555
	v_ashrrev_i32_e32 v67, 4, v0
	s_waitcnt lgkmcnt(0)
	v_and_b32_e32 v1, 15, v0
	v_bfe_u32 v4, v0, 4, 2
	v_lshlrev_b32_e32 v0, 3, v0
	v_and_b32_e32 v0, 0x78, v0
	v_lshlrev_b32_e32 v60, 1, v0
	v_mov_b32_e32 v0, 0
	v_mov_b32_e32 v61, v0
	s_lshl_b32 s3, s0, 4
	s_lshl_b32 s0, s0, 3
	v_lshl_add_u64 v[2:3], s[80:81], 0, v[60:61]
	s_mov_b64 s[4:5], 0x81150000
	s_and_b32 s3, s3, 48
	s_andn2_b32 s0, s0, 31
	v_lshl_add_u64 v[62:63], v[2:3], 0, s[4:5]
	s_movk_i32 s1, 0x88
	v_or_b32_e32 v3, s3, v1
	v_or_b32_e32 v6, s0, v1
	v_mul_lo_u32 v2, v67, s1
	v_mul_u32_u24_e32 v3, 0x88, v3
	v_lshlrev_b32_e32 v5, 3, v4
	v_mul_lo_u32 v7, v6, s1
	v_lshlrev_b32_e32 v68, 4, v1
	v_mbcnt_lo_u32_b32 v1, -1, 0
	v_lshl_add_u64 v[64:65], s[12:13], 0, v[60:61]
	v_add_u32_e32 v61, 0x2000, v6
	v_lshl_or_b32 v66, v4, 2, s3
	v_cmp_eq_u32_e64 s[0:1], 0, v4
	v_mov_b32_e32 v69, v0
	s_movk_i32 s3, 0x5600
	v_mov_b64_e32 v[70:71], s[80:81]
	s_mov_b64 s[4:5], 0x300
	v_lshlrev_b32_e32 v76, 1, v2
	v_lshlrev_b32_e32 v77, 1, v3
	v_lshlrev_b32_e32 v78, 1, v5
	v_lshlrev_b32_e32 v79, 1, v7
	v_mbcnt_hi_u32_b32 v80, -1, v1
	s_and_b32 s98, s2, 7
	s_lshl_b32 s98, s98, 5
	s_lshr_b32 s12, s2, 3
	s_add_i32 s12, s12, s98
	s_branch .LBB0_1541

.LBB0_1654:
	v_mbcnt_lo_u32_b32 v0, -1, 0
	v_mbcnt_hi_u32_b32 v0, -1, v0
	v_readlane_b32 s0, v254, 10
	v_readlane_b32 s2, v255, 42
	s_cmpk_gt_i32 s2, 0xff
	v_add_u32_e32 v0, s0, v0
	s_mov_b32 s0, s75
	v_readlane_b32 s3, v255, 43
	s_cbranch_scc1 .LBB0_1671
	v_ashrrev_i32_e32 v65, 4, v0
	s_waitcnt lgkmcnt(0)
	v_and_b32_e32 v1, 15, v0
	v_bfe_u32 v4, v0, 4, 2
	v_lshlrev_b32_e32 v0, 3, v0
	v_and_b32_e32 v0, 0x78, v0
	s_waitcnt vmcnt(0)
	v_lshlrev_b32_e32 v58, 1, v0
	v_mov_b32_e32 v0, 0
	v_mov_b32_e32 v59, v0
	s_lshl_b32 s3, s0, 4
	s_lshl_b32 s0, s0, 3
	v_lshl_add_u64 v[2:3], s[80:81], 0, v[58:59]
	s_mov_b64 s[4:5], 0x3bd00000
	s_and_b32 s3, s3, 48
	s_andn2_b32 s0, s0, 31
	v_lshl_add_u64 v[60:61], v[2:3], 0, s[4:5]
	s_movk_i32 s1, 0x88
	v_or_b32_e32 v3, s3, v1
	v_or_b32_e32 v6, s0, v1
	v_lshl_add_u64 v[62:63], s[14:15], 0, v[58:59]
	v_mul_lo_u32 v2, v65, s1
	v_mul_u32_u24_e32 v3, 0x88, v3
	v_lshlrev_b32_e32 v5, 3, v4
	v_mul_lo_u32 v7, v6, s1
	v_lshlrev_b32_e32 v66, 4, v1
	v_mbcnt_lo_u32_b32 v1, -1, 0
	v_readlane_b32 s14, v255, 42
	v_add_u32_e32 v59, 0x2000, v6
	v_lshl_or_b32 v64, v4, 2, s3
	v_cmp_eq_u32_e64 s[0:1], 0, v4
	v_mov_b32_e32 v67, v0
	s_mov_b32 s3, 0x40000
	s_mov_b64 s[4:5], 0x300
	v_mov_b32_e32 v72, 0x358637bd
	s_mov_b32 s16, 0x800000
	v_lshlrev_b32_e32 v73, 1, v2
	v_lshlrev_b32_e32 v74, 1, v3
	v_lshlrev_b32_e32 v75, 1, v5
	v_lshlrev_b32_e32 v76, 1, v7
	v_mbcnt_hi_u32_b32 v77, -1, v1
	s_and_b32 s98, s14, 7
	s_lshl_b32 s98, s98, 5
	s_lshr_b32 s17, s14, 3
	s_add_i32 s17, s17, s98
	v_readlane_b32 s15, v255, 43
	s_branch .LBB0_1657

.LBB0_2793:
	v_mbcnt_lo_u32_b32 v0, -1, 0
	v_mbcnt_hi_u32_b32 v0, -1, v0
	v_readlane_b32 s0, v254, 10
	v_readlane_b32 s2, v255, 42
	s_cmpk_gt_i32 s2, 0xff
	v_add_u32_e32 v0, s0, v0
	s_mov_b32 s0, s75
	v_readlane_b32 s3, v255, 43
	s_cbranch_scc1 .LBB0_2810
	v_ashrrev_i32_e32 v67, 4, v0
	s_waitcnt lgkmcnt(0)
	v_and_b32_e32 v1, 15, v0
	v_bfe_u32 v4, v0, 4, 2
	v_lshlrev_b32_e32 v0, 3, v0
	v_and_b32_e32 v0, 0x78, v0
	v_lshlrev_b32_e32 v60, 1, v0
	v_mov_b32_e32 v0, 0
	v_mov_b32_e32 v61, v0
	s_lshl_b32 s3, s0, 4
	s_lshl_b32 s0, s0, 3
	v_lshl_add_u64 v[2:3], s[80:81], 0, v[60:61]
	s_mov_b64 s[4:5], 0x4f890000
	s_and_b32 s3, s3, 48
	s_andn2_b32 s0, s0, 31
	v_lshl_add_u64 v[62:63], v[2:3], 0, s[4:5]
	s_movk_i32 s1, 0x88
	v_or_b32_e32 v3, s3, v1
	v_or_b32_e32 v6, s0, v1
	v_lshl_add_u64 v[64:65], s[10:11], 0, v[60:61]
	v_mul_lo_u32 v2, v67, s1
	v_mul_u32_u24_e32 v3, 0x88, v3
	v_lshlrev_b32_e32 v5, 3, v4
	v_mul_lo_u32 v7, v6, s1
	v_lshlrev_b32_e32 v68, 4, v1
	v_mbcnt_lo_u32_b32 v1, -1, 0
	v_readlane_b32 s10, v255, 42
	v_add_u32_e32 v61, 0x2000, v6
	v_lshl_or_b32 v66, v4, 2, s3
	v_cmp_eq_u32_e64 s[0:1], 0, v4
	v_mov_b32_e32 v69, v0
	s_mov_b32 s3, 0x40000
	s_mov_b64 s[4:5], 0x300
	v_lshlrev_b32_e32 v74, 1, v2
	v_lshlrev_b32_e32 v75, 1, v3
	v_lshlrev_b32_e32 v76, 1, v5
	v_lshlrev_b32_e32 v77, 1, v7
	v_mbcnt_hi_u32_b32 v78, -1, v1
	s_and_b32 s98, s10, 7
	s_lshl_b32 s98, s98, 5
	s_lshr_b32 s12, s10, 3
	s_add_i32 s12, s12, s98
	v_readlane_b32 s11, v255, 43
	s_branch .LBB0_2796

.LBB0_3110:
	v_mbcnt_lo_u32_b32 v0, -1, 0
	v_mbcnt_hi_u32_b32 v0, -1, v0
	v_readlane_b32 s0, v254, 10
	v_readlane_b32 s2, v255, 42
	s_cmpk_gt_i32 s2, 0xff
	v_add_u32_e32 v0, s0, v0
	s_mov_b32 s0, s75
	v_readlane_b32 s3, v255, 43
	s_cbranch_scc1 .LBB0_3127
	v_ashrrev_i32_e32 v67, 4, v0
	s_waitcnt lgkmcnt(0)
	v_and_b32_e32 v1, 15, v0
	v_bfe_u32 v4, v0, 4, 2
	v_lshlrev_b32_e32 v0, 3, v0
	v_and_b32_e32 v0, 0x78, v0
	v_lshlrev_b32_e32 v60, 1, v0
	v_mov_b32_e32 v0, 0
	v_mov_b32_e32 v61, v0
	s_lshl_b32 s3, s0, 4
	s_lshl_b32 s0, s0, 3
	v_lshl_add_u64 v[2:3], s[80:81], 0, v[60:61]
	s_mov_b64 s[4:5], 0x81150000
	s_and_b32 s3, s3, 48
	s_andn2_b32 s0, s0, 31
	v_lshl_add_u64 v[62:63], v[2:3], 0, s[4:5]
	s_movk_i32 s1, 0x88
	v_or_b32_e32 v3, s3, v1
	v_or_b32_e32 v6, s0, v1
	v_mul_lo_u32 v2, v67, s1
	v_mul_u32_u24_e32 v3, 0x88, v3
	v_lshlrev_b32_e32 v5, 3, v4
	v_mul_lo_u32 v7, v6, s1
	v_lshlrev_b32_e32 v68, 4, v1
	v_mbcnt_lo_u32_b32 v1, -1, 0
	v_readlane_b32 s6, v255, 42
	v_lshl_add_u64 v[64:65], s[12:13], 0, v[60:61]
	v_add_u32_e32 v61, 0x2000, v6
	v_lshl_or_b32 v66, v4, 2, s3
	v_cmp_eq_u32_e64 s[0:1], 0, v4
	v_mov_b32_e32 v69, v0
	s_movk_i32 s3, 0x5600
	v_mov_b64_e32 v[70:71], s[80:81]
	s_mov_b64 s[4:5], 0x300
	v_lshlrev_b32_e32 v76, 1, v2
	v_lshlrev_b32_e32 v77, 1, v3
	v_lshlrev_b32_e32 v78, 1, v5
	v_lshlrev_b32_e32 v79, 1, v7
	v_mbcnt_hi_u32_b32 v80, -1, v1
	s_and_b32 s98, s6, 7
	s_lshl_b32 s98, s98, 5
	s_lshr_b32 s12, s6, 3
	s_add_i32 s12, s12, s98
	v_readlane_b32 s7, v255, 43
	s_branch .LBB0_3113

.LBB0_3226:
	v_mbcnt_lo_u32_b32 v0, -1, 0
	v_mbcnt_hi_u32_b32 v0, -1, v0
	v_readlane_b32 s0, v254, 10
	v_readlane_b32 s2, v255, 42
	s_cmpk_gt_i32 s2, 0xff
	v_add_u32_e32 v0, s0, v0
	s_mov_b32 s0, s75
	v_readlane_b32 s3, v255, 43
	s_cbranch_scc1 .LBB0_3243
	v_ashrrev_i32_e32 v65, 4, v0
	s_waitcnt lgkmcnt(0)
	v_and_b32_e32 v1, 15, v0
	v_bfe_u32 v4, v0, 4, 2
	v_lshlrev_b32_e32 v0, 3, v0
	v_and_b32_e32 v0, 0x78, v0
	s_waitcnt vmcnt(0)
	v_lshlrev_b32_e32 v58, 1, v0
	v_mov_b32_e32 v0, 0
	v_mov_b32_e32 v59, v0
	s_lshl_b32 s3, s0, 4
	s_lshl_b32 s0, s0, 3
	v_lshl_add_u64 v[2:3], s[80:81], 0, v[58:59]
	s_mov_b64 s[4:5], 0x9df8c000
	s_and_b32 s3, s3, 48
	s_andn2_b32 s0, s0, 31
	v_lshl_add_u64 v[60:61], v[2:3], 0, s[4:5]
	s_movk_i32 s1, 0x88
	v_or_b32_e32 v3, s3, v1
	v_or_b32_e32 v6, s0, v1
	v_lshl_add_u64 v[62:63], s[14:15], 0, v[58:59]
	v_mul_lo_u32 v2, v65, s1
	v_mul_u32_u24_e32 v3, 0x88, v3
	v_lshlrev_b32_e32 v5, 3, v4
	v_mul_lo_u32 v7, v6, s1
	v_lshlrev_b32_e32 v66, 4, v1
	v_mbcnt_lo_u32_b32 v1, -1, 0
	v_readlane_b32 s14, v255, 42
	v_add_u32_e32 v59, 0x2000, v6
	v_lshl_or_b32 v64, v4, 2, s3
	v_cmp_eq_u32_e64 s[0:1], 0, v4
	v_mov_b32_e32 v67, v0
	s_mov_b32 s3, 0x40000
	s_mov_b64 s[4:5], 0x300
	v_mov_b32_e32 v72, 0x358637bd
	s_mov_b32 s16, 0x800000
	v_lshlrev_b32_e32 v73, 1, v2
	v_lshlrev_b32_e32 v74, 1, v3
	v_lshlrev_b32_e32 v75, 1, v5
	v_lshlrev_b32_e32 v76, 1, v7
	v_mbcnt_hi_u32_b32 v77, -1, v1
	s_and_b32 s98, s14, 7
	s_lshl_b32 s98, s98, 5
	s_lshr_b32 s17, s14, 3
	s_add_i32 s17, s17, s98
	v_readlane_b32 s15, v255, 43
	s_branch .LBB0_3229
